# attention main KV loop hand-scheduled: 3-deep K-fragment ring, double-buffered V fragments, counted lgkmcnt, branchy rare rescale
# speedup vs baseline: 1.0263x; 1.0263x over previous
.LBB0_485:
	s_or_b64 exec, exec, s[12:13]
	v_lshrrev_b32_e32 v8, 3, v165
	v_and_b32_e32 v8, 2, v8
	v_bfe_u32 v9, v165, 1, 1
	v_bfe_u32 v7, v165, 2, 2
	v_or_b32_e32 v10, v8, v9
	v_lshlrev_b32_e32 v166, 2, v4
	v_lshlrev_b32_e32 v11, 3, v165
	v_and_b32_e32 v11, 8, v11
	v_or_b32_e32 v13, v166, v7
	v_bitop3_b32 v8, v8, v4, v9 bitop3:0x36
	v_bitop3_b32 v10, v4, v10, 2 bitop3:0x36
	v_lshlrev_b32_e32 v3, 2, v165
	v_lshlrev_b32_e32 v12, 6, v7
	v_lshlrev_b32_e32 v13, 8, v13
	v_lshlrev_b32_e32 v8, 4, v8
	v_lshl_or_b32 v10, v10, 4, v11
	s_waitcnt vmcnt(0)
	v_or3_b32 v8, v13, v8, v11
	v_xor_b32_e32 v9, 64, v12
	v_xor_b32_e32 v14, 0x80, v12
	v_xor_b32_e32 v15, 0xc0, v12
	v_or3_b32 v10, v13, v10, s73
	v_and_b32_e32 v3, 12, v3
	v_and_b32_e32 v167, 31, v165
	v_or_b32_e32 v155, v8, v12
	v_or_b32_e32 v168, v8, v9
	v_or_b32_e32 v169, v8, v14
	v_or_b32_e32 v170, v8, v15
	v_or_b32_e32 v8, 2, v4
	v_add_u32_e32 v172, v10, v9
	v_or_b32_e32 v9, v3, v7
	v_bitop3_b32 v3, v3, v4, v7 bitop3:0x36
	v_lshlrev_b32_e32 v184, 8, v167
	v_add_u32_e32 v171, v10, v12
	v_add_u32_e32 v173, v10, v14
	v_add_u32_e32 v174, v10, v15
	v_lshlrev_b32_e32 v176, 6, v167
	v_lshlrev_b32_e32 v189, 4, v3
	s_cmp_eq_u32 s15, 1
	v_xor_b32_e32 v188, v8, v9
	v_bitop3_b32 v187, v4, v9, 4 bitop3:0x36
	v_bitop3_b32 v186, v4, v9, 6 bitop3:0x36
	v_bitop3_b32 v185, v4, v9, 8 bitop3:0x36
	v_bitop3_b32 v182, v4, v9, 10 bitop3:0x36
	v_bitop3_b32 v180, v4, v9, 12 bitop3:0x36
	v_bitop3_b32 v179, v4, v9, 14 bitop3:0x36
	v_xor_b32_e32 v178, v4, v7
	v_xor_b32_e32 v177, v8, v7
	s_waitcnt vmcnt(0) lgkmcnt(0)
	s_barrier
	s_cbranch_scc1 .LBB0_493
	v_and_b32_e32 v3, 3, v6
	v_lshlrev_b32_e32 v6, 4, v3
	v_mov_b32_e32 v7, v1
	v_mov_b32_e32 v3, v1
	v_lshl_add_u64 v[2:3], v[6:7], 0, v[2:3]
	v_mad_i64_i32 v[4:5], s[12:13], v5, s71, 0
	v_lshl_add_u64 v[2:3], s[10:11], 0, v[2:3]
	v_lshl_add_u64 v[160:161], v[2:3], 0, s[58:59]
	v_lshl_add_u64 v[2:3], v[4:5], 0, v[0:1]
	v_lshl_add_u64 v[2:3], s[10:11], 0, v[2:3]
	v_mov_b32_e32 v14, v1
	v_mov_b32_e32 v15, v1
	v_lshl_add_u64 v[162:163], v[2:3], 0, s[60:61]
	v_mov_b32_e32 v0, v1
	v_mov_b32_e32 v2, v1
	v_mov_b32_e32 v3, v1
	v_mov_b32_e32 v4, v1
	v_mov_b32_e32 v5, v1
	v_mov_b32_e32 v6, v1
	v_mov_b32_e32 v8, v1
	v_mov_b32_e32 v9, v1
	v_mov_b32_e32 v10, v1
	v_mov_b32_e32 v11, v1
	v_mov_b32_e32 v12, v1
	v_mov_b32_e32 v13, v1
	v_mov_b64_e32 v[78:79], v[14:15]
	v_mov_b64_e32 v[62:63], v[14:15]
	v_mov_b64_e32 v[46:47], v[14:15]
	v_mov_b64_e32 v[30:31], v[14:15]
	v_lshlrev_b32_e32 v190, 4, v188
	v_lshlrev_b32_e32 v191, 4, v187
	v_lshlrev_b32_e32 v192, 4, v186
	v_lshlrev_b32_e32 v193, 4, v185
	v_lshlrev_b32_e32 v194, 4, v182
	v_lshlrev_b32_e32 v195, 4, v180
	v_lshlrev_b32_e32 v196, 4, v179
	v_lshlrev_b32_e32 v198, 4, v178
	v_lshlrev_b32_e32 v199, 4, v177
	s_add_i32 s12, s15, -1
	s_mov_b32 s13, 0
	v_mov_b32_e32 v175, 0xf149f2ca
	v_mov_b32_e32 v200, 0
	v_mov_b64_e32 v[76:77], v[12:13]
	v_mov_b64_e32 v[74:75], v[10:11]
	v_mov_b64_e32 v[72:73], v[8:9]
	v_mov_b64_e32 v[70:71], v[6:7]
	v_mov_b64_e32 v[68:69], v[4:5]
	v_mov_b64_e32 v[66:67], v[2:3]
	v_mov_b64_e32 v[64:65], v[0:1]
	v_mov_b64_e32 v[60:61], v[12:13]
	v_mov_b64_e32 v[58:59], v[10:11]
	v_mov_b64_e32 v[56:57], v[8:9]
	v_mov_b64_e32 v[54:55], v[6:7]
	v_mov_b64_e32 v[52:53], v[4:5]
	v_mov_b64_e32 v[50:51], v[2:3]
	v_mov_b64_e32 v[48:49], v[0:1]
	v_mov_b64_e32 v[44:45], v[12:13]
	v_mov_b64_e32 v[42:43], v[10:11]
	v_mov_b64_e32 v[40:41], v[8:9]
	v_mov_b64_e32 v[38:39], v[6:7]
	v_mov_b64_e32 v[36:37], v[4:5]
	v_mov_b64_e32 v[34:35], v[2:3]
	v_mov_b64_e32 v[32:33], v[0:1]
	v_mov_b64_e32 v[28:29], v[12:13]
	v_mov_b64_e32 v[26:27], v[10:11]
	v_mov_b64_e32 v[24:25], v[8:9]
	v_mov_b64_e32 v[22:23], v[6:7]
	v_mov_b64_e32 v[20:21], v[4:5]
	v_mov_b64_e32 v[18:19], v[2:3]
	v_mov_b64_e32 v[16:17], v[0:1]
	v_add_u32_e32 v201, v184, v189
	v_add_u32_e32 v190, v184, v190
	v_add_u32_e32 v191, v184, v191
	v_add_u32_e32 v192, v184, v192
	v_add_u32_e32 v193, v184, v193
	v_add_u32_e32 v194, v184, v194
	v_add_u32_e32 v195, v184, v195
	v_add_u32_e32 v196, v184, v196
	v_add_u32_e32 v198, v176, v198
	v_add_u32_e32 v199, v176, v199
	v_readfirstlane_b32 s16, v181
	v_mov_b32_e32 v183, v175
	v_mov_b32_e32 v175, v200
.Lat1_loop:
	s_add_u32 m0, s16, 20480
	v_lshl_add_u64 v[202:203], v[162:163], 0, s[54:55]
	global_load_lds_dwordx4 v[162:163], off
	s_add_u32 m0, s16, 28672
	s_nop 0
	global_load_lds_dwordx4 v[202:203], off
	s_cmp_eq_u64 s[6:7], 0
	s_cbranch_scc1 .Lat1_norope_e
	s_add_u32 m0, s16, 36864
	s_nop 0
	global_load_lds_dwordx4 v[160:161], off
.Lat1_norope_e:
	ds_read_b128 v[220:223], v201 offset:0
	ds_read_b128 v[224:227], v201 offset:8192
	ds_read_b128 v[228:231], v190 offset:0
	ds_read_b128 v[232:235], v190 offset:8192
	ds_read_b128 v[236:239], v191 offset:0
	ds_read_b128 v[240:243], v191 offset:8192
	s_waitcnt lgkmcnt(4)
	v_mfma_f32_32x32x16_bf16 v[96:111], v[220:223], v[148:151], 0
	v_mfma_f32_32x32x16_bf16 v[80:95], v[224:227], v[148:151], 0
	ds_read_b128 v[220:223], v192 offset:0
	ds_read_b128 v[224:227], v192 offset:8192
	s_waitcnt lgkmcnt(4)
	v_mfma_f32_32x32x16_bf16 v[96:111], v[228:231], v[144:147], v[96:111]
	v_mfma_f32_32x32x16_bf16 v[80:95], v[232:235], v[144:147], v[80:95]
	ds_read_b128 v[228:231], v193 offset:0
	ds_read_b128 v[232:235], v193 offset:8192
	s_waitcnt lgkmcnt(4)
	v_mfma_f32_32x32x16_bf16 v[96:111], v[236:239], v[140:143], v[96:111]
	v_mfma_f32_32x32x16_bf16 v[80:95], v[240:243], v[140:143], v[80:95]
	ds_read_b128 v[236:239], v194 offset:0
	ds_read_b128 v[240:243], v194 offset:8192
	s_waitcnt lgkmcnt(4)
	v_mfma_f32_32x32x16_bf16 v[96:111], v[220:223], v[136:139], v[96:111]
	v_mfma_f32_32x32x16_bf16 v[80:95], v[224:227], v[136:139], v[80:95]
	ds_read_b128 v[220:223], v195 offset:0
	ds_read_b128 v[224:227], v195 offset:8192
	s_waitcnt lgkmcnt(4)
	v_mfma_f32_32x32x16_bf16 v[96:111], v[228:231], v[132:135], v[96:111]
	v_mfma_f32_32x32x16_bf16 v[80:95], v[232:235], v[132:135], v[80:95]
	ds_read_b128 v[228:231], v196 offset:0
	ds_read_b128 v[232:235], v196 offset:8192
	s_waitcnt lgkmcnt(4)
	v_mfma_f32_32x32x16_bf16 v[96:111], v[236:239], v[128:131], v[96:111]
	v_mfma_f32_32x32x16_bf16 v[80:95], v[240:243], v[128:131], v[80:95]
	ds_read_b128 v[236:239], v198 offset:16384
	ds_read_b128 v[240:243], v198 offset:18432
	s_waitcnt lgkmcnt(4)
	v_mfma_f32_32x32x16_bf16 v[96:111], v[220:223], v[124:127], v[96:111]
	v_mfma_f32_32x32x16_bf16 v[80:95], v[224:227], v[124:127], v[80:95]
	ds_read_b128 v[220:223], v199 offset:16384
	ds_read_b128 v[224:227], v199 offset:18432
	s_waitcnt lgkmcnt(4)
	v_mfma_f32_32x32x16_bf16 v[96:111], v[228:231], v[120:123], v[96:111]
	v_mfma_f32_32x32x16_bf16 v[80:95], v[232:235], v[120:123], v[80:95]
	s_waitcnt lgkmcnt(2)
	v_mfma_f32_32x32x16_bf16 v[96:111], v[236:239], v[116:119], v[96:111]
	v_mfma_f32_32x32x16_bf16 v[80:95], v[240:243], v[116:119], v[80:95]
	s_waitcnt lgkmcnt(0)
	v_mfma_f32_32x32x16_bf16 v[96:111], v[220:223], v[112:115], v[96:111]
	v_mfma_f32_32x32x16_bf16 v[80:95], v[224:227], v[112:115], v[80:95]
	ds_read_b64_tr_b16 v[220:221], v155 offset:0
	ds_read_b64_tr_b16 v[224:225], v168 offset:0
	ds_read_b64_tr_b16 v[228:229], v169 offset:0
	ds_read_b64_tr_b16 v[232:233], v170 offset:0
	ds_read_b64_tr_b16 v[222:223], v171 offset:0
	ds_read_b64_tr_b16 v[226:227], v172 offset:0
	ds_read_b64_tr_b16 v[230:231], v173 offset:0
	ds_read_b64_tr_b16 v[234:235], v174 offset:0
	v_add_f32_e32 v2, 2.0, v183
	s_nop 4
	v_max3_f32 v14, v96, v97, v98
	v_max3_f32 v14, v14, v99, v100
	v_max3_f32 v14, v14, v101, v102
	v_max3_f32 v14, v14, v103, v104
	v_max3_f32 v14, v14, v105, v106
	v_max3_f32 v14, v14, v107, v108
	v_max3_f32 v14, v14, v109, v110
	v_max3_f32 v14, v14, v111, v80
	v_max3_f32 v14, v14, v81, v82
	v_max3_f32 v14, v14, v83, v84
	v_max3_f32 v14, v14, v85, v86
	v_max3_f32 v14, v14, v87, v88
	v_max3_f32 v14, v14, v89, v90
	v_max3_f32 v14, v14, v91, v92
	v_max3_f32 v14, v14, v93, v94
	v_max_f32_e32 v14, v14, v95
	v_mov_b32_e32 v15, v14
	s_nop 1
	v_permlane32_swap_b32_e32 v14, v15
	v_max_f32_e32 v14, v14, v15
	v_cmp_gt_f32_e32 vcc, v14, v2
	s_cbranch_vccnz .Lat1_rare_e
.Lat1_common_e:
	s_waitcnt lgkmcnt(7)
	ds_read_b64_tr_b16 v[236:237], v155 offset:4096
	ds_read_b64_tr_b16 v[240:241], v168 offset:4096
	ds_read_b64_tr_b16 v[244:245], v169 offset:4096
	ds_read_b64_tr_b16 v[204:205], v170 offset:4096
	ds_read_b64_tr_b16 v[238:239], v171 offset:4096
	ds_read_b64_tr_b16 v[242:243], v172 offset:4096
	ds_read_b64_tr_b16 v[246:247], v173 offset:4096
	ds_read_b64_tr_b16 v[206:207], v174 offset:4096
	v_sub_f32_e32 v96, v96, v183
	v_sub_f32_e32 v97, v97, v183
	v_exp_f32_e32 v96, v96
	v_exp_f32_e32 v97, v97
	v_sub_f32_e32 v98, v98, v183
	v_sub_f32_e32 v99, v99, v183
	v_exp_f32_e32 v98, v98
	v_exp_f32_e32 v99, v99
	v_cvt_pk_bf16_f32 v6, v96, v97
	v_sub_f32_e32 v100, v100, v183
	v_sub_f32_e32 v101, v101, v183
	v_exp_f32_e32 v100, v100
	v_exp_f32_e32 v101, v101
	v_add_f32_e32 v175, v175, v96
	v_cvt_pk_bf16_f32 v7, v98, v99
	v_sub_f32_e32 v102, v102, v183
	v_sub_f32_e32 v103, v103, v183
	v_exp_f32_e32 v102, v102
	v_exp_f32_e32 v103, v103
	v_add_f32_e32 v175, v175, v97
	v_add_f32_e32 v175, v175, v98
	v_cvt_pk_bf16_f32 v8, v100, v101
	v_add_f32_e32 v175, v175, v99
	v_add_f32_e32 v175, v175, v100
	v_add_f32_e32 v175, v175, v101
	v_cvt_pk_bf16_f32 v9, v102, v103
	v_add_f32_e32 v175, v175, v102
	v_add_f32_e32 v175, v175, v103
	s_waitcnt lgkmcnt(8)
	v_mfma_f32_32x32x16_bf16 v[64:79], v[220:223], v[6:9], v[64:79]
	v_sub_f32_e32 v104, v104, v183
	v_sub_f32_e32 v105, v105, v183
	v_exp_f32_e32 v104, v104
	v_exp_f32_e32 v105, v105
	v_sub_f32_e32 v106, v106, v183
	v_sub_f32_e32 v107, v107, v183
	v_exp_f32_e32 v106, v106
	v_mfma_f32_32x32x16_bf16 v[48:63], v[224:227], v[6:9], v[48:63]
	v_exp_f32_e32 v107, v107
	v_cvt_pk_bf16_f32 v10, v104, v105
	v_sub_f32_e32 v108, v108, v183
	v_sub_f32_e32 v109, v109, v183
	v_exp_f32_e32 v108, v108
	v_exp_f32_e32 v109, v109
	v_add_f32_e32 v175, v175, v104
	v_mfma_f32_32x32x16_bf16 v[32:47], v[228:231], v[6:9], v[32:47]
	v_cvt_pk_bf16_f32 v11, v106, v107
	v_sub_f32_e32 v110, v110, v183
	v_sub_f32_e32 v111, v111, v183
	v_exp_f32_e32 v110, v110
	v_exp_f32_e32 v111, v111
	v_add_f32_e32 v175, v175, v105
	v_add_f32_e32 v175, v175, v106
	v_mfma_f32_32x32x16_bf16 v[16:31], v[232:235], v[6:9], v[16:31]
	v_cvt_pk_bf16_f32 v12, v108, v109
	v_add_f32_e32 v175, v175, v107
	v_add_f32_e32 v175, v175, v108
	v_add_f32_e32 v175, v175, v109
	v_cvt_pk_bf16_f32 v13, v110, v111
	v_add_f32_e32 v175, v175, v110
	v_add_f32_e32 v175, v175, v111
	s_waitcnt lgkmcnt(7)
	ds_read_b64_tr_b16 v[220:221], v155 offset:8192
	ds_read_b64_tr_b16 v[224:225], v168 offset:8192
	ds_read_b64_tr_b16 v[228:229], v169 offset:8192
	ds_read_b64_tr_b16 v[232:233], v170 offset:8192
	ds_read_b64_tr_b16 v[222:223], v171 offset:8192
	ds_read_b64_tr_b16 v[226:227], v172 offset:8192
	ds_read_b64_tr_b16 v[230:231], v173 offset:8192
	ds_read_b64_tr_b16 v[234:235], v174 offset:8192
	s_waitcnt lgkmcnt(8)
	v_mfma_f32_32x32x16_bf16 v[64:79], v[236:239], v[10:13], v[64:79]
	v_sub_f32_e32 v80, v80, v183
	v_sub_f32_e32 v81, v81, v183
	v_exp_f32_e32 v80, v80
	v_exp_f32_e32 v81, v81
	v_sub_f32_e32 v82, v82, v183
	v_sub_f32_e32 v83, v83, v183
	v_exp_f32_e32 v82, v82
	v_mfma_f32_32x32x16_bf16 v[48:63], v[240:243], v[10:13], v[48:63]
	v_exp_f32_e32 v83, v83
	v_cvt_pk_bf16_f32 v6, v80, v81
	v_sub_f32_e32 v84, v84, v183
	v_sub_f32_e32 v85, v85, v183
	v_exp_f32_e32 v84, v84
	v_exp_f32_e32 v85, v85
	v_add_f32_e32 v175, v175, v80
	v_mfma_f32_32x32x16_bf16 v[32:47], v[244:247], v[10:13], v[32:47]
	v_cvt_pk_bf16_f32 v7, v82, v83
	v_sub_f32_e32 v86, v86, v183
	v_sub_f32_e32 v87, v87, v183
	v_exp_f32_e32 v86, v86
	v_exp_f32_e32 v87, v87
	v_add_f32_e32 v175, v175, v81
	v_add_f32_e32 v175, v175, v82
	v_mfma_f32_32x32x16_bf16 v[16:31], v[204:207], v[10:13], v[16:31]
	v_cvt_pk_bf16_f32 v8, v84, v85
	v_add_f32_e32 v175, v175, v83
	v_add_f32_e32 v175, v175, v84
	v_add_f32_e32 v175, v175, v85
	v_cvt_pk_bf16_f32 v9, v86, v87
	v_add_f32_e32 v175, v175, v86
	v_add_f32_e32 v175, v175, v87
	s_waitcnt lgkmcnt(7)
	ds_read_b64_tr_b16 v[236:237], v155 offset:12288
	ds_read_b64_tr_b16 v[240:241], v168 offset:12288
	ds_read_b64_tr_b16 v[244:245], v169 offset:12288
	ds_read_b64_tr_b16 v[204:205], v170 offset:12288
	ds_read_b64_tr_b16 v[238:239], v171 offset:12288
	ds_read_b64_tr_b16 v[242:243], v172 offset:12288
	ds_read_b64_tr_b16 v[246:247], v173 offset:12288
	ds_read_b64_tr_b16 v[206:207], v174 offset:12288
	s_waitcnt lgkmcnt(8)
	v_mfma_f32_32x32x16_bf16 v[64:79], v[220:223], v[6:9], v[64:79]
	v_sub_f32_e32 v88, v88, v183
	v_sub_f32_e32 v89, v89, v183
	v_exp_f32_e32 v88, v88
	v_exp_f32_e32 v89, v89
	v_sub_f32_e32 v90, v90, v183
	v_sub_f32_e32 v91, v91, v183
	v_exp_f32_e32 v90, v90
	v_mfma_f32_32x32x16_bf16 v[48:63], v[224:227], v[6:9], v[48:63]
	v_exp_f32_e32 v91, v91
	v_cvt_pk_bf16_f32 v10, v88, v89
	v_sub_f32_e32 v92, v92, v183
	v_sub_f32_e32 v93, v93, v183
	v_exp_f32_e32 v92, v92
	v_exp_f32_e32 v93, v93
	v_add_f32_e32 v175, v175, v88
	v_mfma_f32_32x32x16_bf16 v[32:47], v[228:231], v[6:9], v[32:47]
	v_cvt_pk_bf16_f32 v11, v90, v91
	v_sub_f32_e32 v94, v94, v183
	v_sub_f32_e32 v95, v95, v183
	v_exp_f32_e32 v94, v94
	v_exp_f32_e32 v95, v95
	v_add_f32_e32 v175, v175, v89
	v_add_f32_e32 v175, v175, v90
	v_mfma_f32_32x32x16_bf16 v[16:31], v[232:235], v[6:9], v[16:31]
	v_cvt_pk_bf16_f32 v12, v92, v93
	v_add_f32_e32 v175, v175, v91
	v_add_f32_e32 v175, v175, v92
	v_add_f32_e32 v175, v175, v93
	v_cvt_pk_bf16_f32 v13, v94, v95
	v_add_f32_e32 v175, v175, v94
	v_add_f32_e32 v175, v175, v95
	s_waitcnt lgkmcnt(0)
	s_waitcnt vmcnt(0)
	s_barrier
	v_mfma_f32_32x32x16_bf16 v[64:79], v[236:239], v[10:13], v[64:79]
	v_mfma_f32_32x32x16_bf16 v[48:63], v[240:243], v[10:13], v[48:63]
	v_mfma_f32_32x32x16_bf16 v[32:47], v[244:247], v[10:13], v[32:47]
	v_mfma_f32_32x32x16_bf16 v[16:31], v[204:207], v[10:13], v[16:31]
	v_lshl_add_u64 v[160:161], v[160:161], 0, s[60:61]
	v_lshl_add_u64 v[162:163], v[162:163], 0, s[60:61]
	s_add_i32 s13, s13, 1
	s_cmp_eq_u32 s12, s13
	s_cbranch_scc1 .Lat1_exit
	s_add_u32 m0, s16, 0
	v_lshl_add_u64 v[202:203], v[162:163], 0, s[54:55]
	global_load_lds_dwordx4 v[162:163], off
	s_add_u32 m0, s16, 8192
	s_nop 0
	global_load_lds_dwordx4 v[202:203], off
	s_cmp_eq_u64 s[6:7], 0
	s_cbranch_scc1 .Lat1_norope_o
	s_add_u32 m0, s16, 16384
	s_nop 0
	global_load_lds_dwordx4 v[160:161], off
.Lat1_norope_o:
	ds_read_b128 v[220:223], v201 offset:20480
	ds_read_b128 v[224:227], v201 offset:28672
	ds_read_b128 v[228:231], v190 offset:20480
	ds_read_b128 v[232:235], v190 offset:28672
	ds_read_b128 v[236:239], v191 offset:20480
	ds_read_b128 v[240:243], v191 offset:28672
	s_waitcnt lgkmcnt(4)
	v_mfma_f32_32x32x16_bf16 v[96:111], v[220:223], v[148:151], 0
	v_mfma_f32_32x32x16_bf16 v[80:95], v[224:227], v[148:151], 0
	ds_read_b128 v[220:223], v192 offset:20480
	ds_read_b128 v[224:227], v192 offset:28672
	s_waitcnt lgkmcnt(4)
	v_mfma_f32_32x32x16_bf16 v[96:111], v[228:231], v[144:147], v[96:111]
	v_mfma_f32_32x32x16_bf16 v[80:95], v[232:235], v[144:147], v[80:95]
	ds_read_b128 v[228:231], v193 offset:20480
	ds_read_b128 v[232:235], v193 offset:28672
	s_waitcnt lgkmcnt(4)
	v_mfma_f32_32x32x16_bf16 v[96:111], v[236:239], v[140:143], v[96:111]
	v_mfma_f32_32x32x16_bf16 v[80:95], v[240:243], v[140:143], v[80:95]
	ds_read_b128 v[236:239], v194 offset:20480
	ds_read_b128 v[240:243], v194 offset:28672
	s_waitcnt lgkmcnt(4)
	v_mfma_f32_32x32x16_bf16 v[96:111], v[220:223], v[136:139], v[96:111]
	v_mfma_f32_32x32x16_bf16 v[80:95], v[224:227], v[136:139], v[80:95]
	ds_read_b128 v[220:223], v195 offset:20480
	ds_read_b128 v[224:227], v195 offset:28672
	s_waitcnt lgkmcnt(4)
	v_mfma_f32_32x32x16_bf16 v[96:111], v[228:231], v[132:135], v[96:111]
	v_mfma_f32_32x32x16_bf16 v[80:95], v[232:235], v[132:135], v[80:95]
	ds_read_b128 v[228:231], v196 offset:20480
	ds_read_b128 v[232:235], v196 offset:28672
	s_waitcnt lgkmcnt(4)
	v_mfma_f32_32x32x16_bf16 v[96:111], v[236:239], v[128:131], v[96:111]
	v_mfma_f32_32x32x16_bf16 v[80:95], v[240:243], v[128:131], v[80:95]
	ds_read_b128 v[236:239], v198 offset:36864
	ds_read_b128 v[240:243], v198 offset:38912
	s_waitcnt lgkmcnt(4)
	v_mfma_f32_32x32x16_bf16 v[96:111], v[220:223], v[124:127], v[96:111]
	v_mfma_f32_32x32x16_bf16 v[80:95], v[224:227], v[124:127], v[80:95]
	ds_read_b128 v[220:223], v199 offset:36864
	ds_read_b128 v[224:227], v199 offset:38912
	s_waitcnt lgkmcnt(4)
	v_mfma_f32_32x32x16_bf16 v[96:111], v[228:231], v[120:123], v[96:111]
	v_mfma_f32_32x32x16_bf16 v[80:95], v[232:235], v[120:123], v[80:95]
	s_waitcnt lgkmcnt(2)
	v_mfma_f32_32x32x16_bf16 v[96:111], v[236:239], v[116:119], v[96:111]
	v_mfma_f32_32x32x16_bf16 v[80:95], v[240:243], v[116:119], v[80:95]
	s_waitcnt lgkmcnt(0)
	v_mfma_f32_32x32x16_bf16 v[96:111], v[220:223], v[112:115], v[96:111]
	v_mfma_f32_32x32x16_bf16 v[80:95], v[224:227], v[112:115], v[80:95]
	ds_read_b64_tr_b16 v[220:221], v155 offset:20480
	ds_read_b64_tr_b16 v[224:225], v168 offset:20480
	ds_read_b64_tr_b16 v[228:229], v169 offset:20480
	ds_read_b64_tr_b16 v[232:233], v170 offset:20480
	ds_read_b64_tr_b16 v[222:223], v171 offset:20480
	ds_read_b64_tr_b16 v[226:227], v172 offset:20480
	ds_read_b64_tr_b16 v[230:231], v173 offset:20480
	ds_read_b64_tr_b16 v[234:235], v174 offset:20480
	v_add_f32_e32 v2, 2.0, v183
	s_nop 4
	v_max3_f32 v14, v96, v97, v98
	v_max3_f32 v14, v14, v99, v100
	v_max3_f32 v14, v14, v101, v102
	v_max3_f32 v14, v14, v103, v104
	v_max3_f32 v14, v14, v105, v106
	v_max3_f32 v14, v14, v107, v108
	v_max3_f32 v14, v14, v109, v110
	v_max3_f32 v14, v14, v111, v80
	v_max3_f32 v14, v14, v81, v82
	v_max3_f32 v14, v14, v83, v84
	v_max3_f32 v14, v14, v85, v86
	v_max3_f32 v14, v14, v87, v88
	v_max3_f32 v14, v14, v89, v90
	v_max3_f32 v14, v14, v91, v92
	v_max3_f32 v14, v14, v93, v94
	v_max_f32_e32 v14, v14, v95
	v_mov_b32_e32 v15, v14
	s_nop 1
	v_permlane32_swap_b32_e32 v14, v15
	v_max_f32_e32 v14, v14, v15
	v_cmp_gt_f32_e32 vcc, v14, v2
	s_cbranch_vccnz .Lat1_rare_o
.Lat1_common_o:
	s_waitcnt lgkmcnt(7)
	ds_read_b64_tr_b16 v[236:237], v155 offset:24576
	ds_read_b64_tr_b16 v[240:241], v168 offset:24576
	ds_read_b64_tr_b16 v[244:245], v169 offset:24576
	ds_read_b64_tr_b16 v[204:205], v170 offset:24576
	ds_read_b64_tr_b16 v[238:239], v171 offset:24576
	ds_read_b64_tr_b16 v[242:243], v172 offset:24576
	ds_read_b64_tr_b16 v[246:247], v173 offset:24576
	ds_read_b64_tr_b16 v[206:207], v174 offset:24576
	v_sub_f32_e32 v96, v96, v183
	v_sub_f32_e32 v97, v97, v183
	v_exp_f32_e32 v96, v96
	v_exp_f32_e32 v97, v97
	v_sub_f32_e32 v98, v98, v183
	v_sub_f32_e32 v99, v99, v183
	v_exp_f32_e32 v98, v98
	v_exp_f32_e32 v99, v99
	v_cvt_pk_bf16_f32 v6, v96, v97
	v_sub_f32_e32 v100, v100, v183
	v_sub_f32_e32 v101, v101, v183
	v_exp_f32_e32 v100, v100
	v_exp_f32_e32 v101, v101
	v_add_f32_e32 v175, v175, v96
	v_cvt_pk_bf16_f32 v7, v98, v99
	v_sub_f32_e32 v102, v102, v183
	v_sub_f32_e32 v103, v103, v183
	v_exp_f32_e32 v102, v102
	v_exp_f32_e32 v103, v103
	v_add_f32_e32 v175, v175, v97
	v_add_f32_e32 v175, v175, v98
	v_cvt_pk_bf16_f32 v8, v100, v101
	v_add_f32_e32 v175, v175, v99
	v_add_f32_e32 v175, v175, v100
	v_add_f32_e32 v175, v175, v101
	v_cvt_pk_bf16_f32 v9, v102, v103
	v_add_f32_e32 v175, v175, v102
	v_add_f32_e32 v175, v175, v103
	s_waitcnt lgkmcnt(8)
	v_mfma_f32_32x32x16_bf16 v[64:79], v[220:223], v[6:9], v[64:79]
	v_sub_f32_e32 v104, v104, v183
	v_sub_f32_e32 v105, v105, v183
	v_exp_f32_e32 v104, v104
	v_exp_f32_e32 v105, v105
	v_sub_f32_e32 v106, v106, v183
	v_sub_f32_e32 v107, v107, v183
	v_exp_f32_e32 v106, v106
	v_mfma_f32_32x32x16_bf16 v[48:63], v[224:227], v[6:9], v[48:63]
	v_exp_f32_e32 v107, v107
	v_cvt_pk_bf16_f32 v10, v104, v105
	v_sub_f32_e32 v108, v108, v183
	v_sub_f32_e32 v109, v109, v183
	v_exp_f32_e32 v108, v108
	v_exp_f32_e32 v109, v109
	v_add_f32_e32 v175, v175, v104
	v_mfma_f32_32x32x16_bf16 v[32:47], v[228:231], v[6:9], v[32:47]
	v_cvt_pk_bf16_f32 v11, v106, v107
	v_sub_f32_e32 v110, v110, v183
	v_sub_f32_e32 v111, v111, v183
	v_exp_f32_e32 v110, v110
	v_exp_f32_e32 v111, v111
	v_add_f32_e32 v175, v175, v105
	v_add_f32_e32 v175, v175, v106
	v_mfma_f32_32x32x16_bf16 v[16:31], v[232:235], v[6:9], v[16:31]
	v_cvt_pk_bf16_f32 v12, v108, v109
	v_add_f32_e32 v175, v175, v107
	v_add_f32_e32 v175, v175, v108
	v_add_f32_e32 v175, v175, v109
	v_cvt_pk_bf16_f32 v13, v110, v111
	v_add_f32_e32 v175, v175, v110
	v_add_f32_e32 v175, v175, v111
	s_waitcnt lgkmcnt(7)
	ds_read_b64_tr_b16 v[220:221], v155 offset:28672
	ds_read_b64_tr_b16 v[224:225], v168 offset:28672
	ds_read_b64_tr_b16 v[228:229], v169 offset:28672
	ds_read_b64_tr_b16 v[232:233], v170 offset:28672
	ds_read_b64_tr_b16 v[222:223], v171 offset:28672
	ds_read_b64_tr_b16 v[226:227], v172 offset:28672
	ds_read_b64_tr_b16 v[230:231], v173 offset:28672
	ds_read_b64_tr_b16 v[234:235], v174 offset:28672
	s_waitcnt lgkmcnt(8)
	v_mfma_f32_32x32x16_bf16 v[64:79], v[236:239], v[10:13], v[64:79]
	v_sub_f32_e32 v80, v80, v183
	v_sub_f32_e32 v81, v81, v183
	v_exp_f32_e32 v80, v80
	v_exp_f32_e32 v81, v81
	v_sub_f32_e32 v82, v82, v183
	v_sub_f32_e32 v83, v83, v183
	v_exp_f32_e32 v82, v82
	v_mfma_f32_32x32x16_bf16 v[48:63], v[240:243], v[10:13], v[48:63]
	v_exp_f32_e32 v83, v83
	v_cvt_pk_bf16_f32 v6, v80, v81
	v_sub_f32_e32 v84, v84, v183
	v_sub_f32_e32 v85, v85, v183
	v_exp_f32_e32 v84, v84
	v_exp_f32_e32 v85, v85
	v_add_f32_e32 v175, v175, v80
	v_mfma_f32_32x32x16_bf16 v[32:47], v[244:247], v[10:13], v[32:47]
	v_cvt_pk_bf16_f32 v7, v82, v83
	v_sub_f32_e32 v86, v86, v183
	v_sub_f32_e32 v87, v87, v183
	v_exp_f32_e32 v86, v86
	v_exp_f32_e32 v87, v87
	v_add_f32_e32 v175, v175, v81
	v_add_f32_e32 v175, v175, v82
	v_mfma_f32_32x32x16_bf16 v[16:31], v[204:207], v[10:13], v[16:31]
	v_cvt_pk_bf16_f32 v8, v84, v85
	v_add_f32_e32 v175, v175, v83
	v_add_f32_e32 v175, v175, v84
	v_add_f32_e32 v175, v175, v85
	v_cvt_pk_bf16_f32 v9, v86, v87
	v_add_f32_e32 v175, v175, v86
	v_add_f32_e32 v175, v175, v87
	s_waitcnt lgkmcnt(7)
	ds_read_b64_tr_b16 v[236:237], v155 offset:32768
	ds_read_b64_tr_b16 v[240:241], v168 offset:32768
	ds_read_b64_tr_b16 v[244:245], v169 offset:32768
	ds_read_b64_tr_b16 v[204:205], v170 offset:32768
	ds_read_b64_tr_b16 v[238:239], v171 offset:32768
	ds_read_b64_tr_b16 v[242:243], v172 offset:32768
	ds_read_b64_tr_b16 v[246:247], v173 offset:32768
	ds_read_b64_tr_b16 v[206:207], v174 offset:32768
	s_waitcnt lgkmcnt(8)
	v_mfma_f32_32x32x16_bf16 v[64:79], v[220:223], v[6:9], v[64:79]
	v_sub_f32_e32 v88, v88, v183
	v_sub_f32_e32 v89, v89, v183
	v_exp_f32_e32 v88, v88
	v_exp_f32_e32 v89, v89
	v_sub_f32_e32 v90, v90, v183
	v_sub_f32_e32 v91, v91, v183
	v_exp_f32_e32 v90, v90
	v_mfma_f32_32x32x16_bf16 v[48:63], v[224:227], v[6:9], v[48:63]
	v_exp_f32_e32 v91, v91
	v_cvt_pk_bf16_f32 v10, v88, v89
	v_sub_f32_e32 v92, v92, v183
	v_sub_f32_e32 v93, v93, v183
	v_exp_f32_e32 v92, v92
	v_exp_f32_e32 v93, v93
	v_add_f32_e32 v175, v175, v88
	v_mfma_f32_32x32x16_bf16 v[32:47], v[228:231], v[6:9], v[32:47]
	v_cvt_pk_bf16_f32 v11, v90, v91
	v_sub_f32_e32 v94, v94, v183
	v_sub_f32_e32 v95, v95, v183
	v_exp_f32_e32 v94, v94
	v_exp_f32_e32 v95, v95
	v_add_f32_e32 v175, v175, v89
	v_add_f32_e32 v175, v175, v90
	v_mfma_f32_32x32x16_bf16 v[16:31], v[232:235], v[6:9], v[16:31]
	v_cvt_pk_bf16_f32 v12, v92, v93
	v_add_f32_e32 v175, v175, v91
	v_add_f32_e32 v175, v175, v92
	v_add_f32_e32 v175, v175, v93
	v_cvt_pk_bf16_f32 v13, v94, v95
	v_add_f32_e32 v175, v175, v94
	v_add_f32_e32 v175, v175, v95
	s_waitcnt lgkmcnt(0)
	s_waitcnt vmcnt(0)
	s_barrier
	v_mfma_f32_32x32x16_bf16 v[64:79], v[236:239], v[10:13], v[64:79]
	v_mfma_f32_32x32x16_bf16 v[48:63], v[240:243], v[10:13], v[48:63]
	v_mfma_f32_32x32x16_bf16 v[32:47], v[244:247], v[10:13], v[32:47]
	v_mfma_f32_32x32x16_bf16 v[16:31], v[204:207], v[10:13], v[16:31]
	v_lshl_add_u64 v[160:161], v[160:161], 0, s[60:61]
	v_lshl_add_u64 v[162:163], v[162:163], 0, s[60:61]
	s_add_i32 s13, s13, 1
	s_cmp_eq_u32 s12, s13
	s_cbranch_scc0 .Lat1_loop
.Lat1_exit:
	s_branch .LBB0_494
.Lat1_rare_e:
	v_max_f32_e32 v2, v183, v14
	v_sub_f32_e32 v0, v183, v2
	v_exp_f32_e32 v0, v0
	v_mov_b32_e32 v183, v2
	s_nop 0
	v_mul_f32_e32 v175, v175, v0
	v_pk_mul_f32 v[78:79], v[78:79], v[0:1] op_sel_hi:[1,0]
	v_pk_mul_f32 v[76:77], v[76:77], v[0:1] op_sel_hi:[1,0]
	v_pk_mul_f32 v[74:75], v[74:75], v[0:1] op_sel_hi:[1,0]
	v_pk_mul_f32 v[72:73], v[72:73], v[0:1] op_sel_hi:[1,0]
	v_pk_mul_f32 v[70:71], v[70:71], v[0:1] op_sel_hi:[1,0]
	v_pk_mul_f32 v[68:69], v[68:69], v[0:1] op_sel_hi:[1,0]
	v_pk_mul_f32 v[66:67], v[66:67], v[0:1] op_sel_hi:[1,0]
	v_pk_mul_f32 v[64:65], v[64:65], v[0:1] op_sel_hi:[1,0]
	v_pk_mul_f32 v[62:63], v[62:63], v[0:1] op_sel_hi:[1,0]
	v_pk_mul_f32 v[60:61], v[60:61], v[0:1] op_sel_hi:[1,0]
	v_pk_mul_f32 v[58:59], v[58:59], v[0:1] op_sel_hi:[1,0]
	v_pk_mul_f32 v[56:57], v[56:57], v[0:1] op_sel_hi:[1,0]
	v_pk_mul_f32 v[54:55], v[54:55], v[0:1] op_sel_hi:[1,0]
	v_pk_mul_f32 v[52:53], v[52:53], v[0:1] op_sel_hi:[1,0]
	v_pk_mul_f32 v[50:51], v[50:51], v[0:1] op_sel_hi:[1,0]
	v_pk_mul_f32 v[48:49], v[48:49], v[0:1] op_sel_hi:[1,0]
	v_pk_mul_f32 v[46:47], v[46:47], v[0:1] op_sel_hi:[1,0]
	v_pk_mul_f32 v[44:45], v[44:45], v[0:1] op_sel_hi:[1,0]
	v_pk_mul_f32 v[42:43], v[42:43], v[0:1] op_sel_hi:[1,0]
	v_pk_mul_f32 v[40:41], v[40:41], v[0:1] op_sel_hi:[1,0]
	v_pk_mul_f32 v[38:39], v[38:39], v[0:1] op_sel_hi:[1,0]
	v_pk_mul_f32 v[36:37], v[36:37], v[0:1] op_sel_hi:[1,0]
	v_pk_mul_f32 v[34:35], v[34:35], v[0:1] op_sel_hi:[1,0]
	v_pk_mul_f32 v[32:33], v[32:33], v[0:1] op_sel_hi:[1,0]
	v_pk_mul_f32 v[30:31], v[30:31], v[0:1] op_sel_hi:[1,0]
	v_pk_mul_f32 v[28:29], v[28:29], v[0:1] op_sel_hi:[1,0]
	v_pk_mul_f32 v[26:27], v[26:27], v[0:1] op_sel_hi:[1,0]
	v_pk_mul_f32 v[24:25], v[24:25], v[0:1] op_sel_hi:[1,0]
	v_pk_mul_f32 v[22:23], v[22:23], v[0:1] op_sel_hi:[1,0]
	v_pk_mul_f32 v[20:21], v[20:21], v[0:1] op_sel_hi:[1,0]
	v_pk_mul_f32 v[18:19], v[18:19], v[0:1] op_sel_hi:[1,0]
	v_pk_mul_f32 v[16:17], v[16:17], v[0:1] op_sel_hi:[1,0]
	s_branch .Lat1_common_e
